# acquire (buffer_inv sc1) issued together with the arrive atomic (waited with vmcnt(1) for the atomic only), so XCD leaders of local barriers need no separate acquire
# baseline (speedup 1.0000x reference)
.LBB0_180:
	s_or_b64 exec, exec, s[12:13]
	buffer_inv sc1
	v_cvt_f32_u32_e32 v5, v3
	s_waitcnt vmcnt(1)
	v_readfirstlane_b32 s2, v4
	v_sub_u32_e32 v4, 0, v3
	v_rcp_iflag_f32_e32 v5, v5
	v_add_u32_e32 v6, s2, v0
	v_mul_f32_e32 v5, 0x4f7ffffe, v5
	v_cvt_u32_f32_e32 v5, v5
	v_mul_lo_u32 v0, v4, v5
	v_mul_hi_u32 v0, v5, v0
	v_add_u32_e32 v0, v5, v0
	v_mul_hi_u32 v0, v6, v0
	v_mul_lo_u32 v4, v0, v3
	v_sub_u32_e32 v4, v6, v4
	v_add_u32_e32 v5, 1, v0
	v_cmp_ge_u32_e32 vcc, v4, v3
	s_nop 1
	v_cndmask_b32_e32 v0, v0, v5, vcc
	v_sub_u32_e32 v5, v4, v3
	v_cndmask_b32_e32 v4, v4, v5, vcc
	v_add_u32_e32 v5, 1, v0
	v_cmp_ge_u32_e32 vcc, v4, v3
	v_add_u32_e32 v4, 1, v6
	s_nop 0
	v_cndmask_b32_e32 v0, v0, v5, vcc
	v_mul_lo_u32 v5, v3, v0
	v_add_u32_e32 v3, v5, v3
	v_cmp_ne_u32_e32 vcc, v4, v3
	s_and_saveexec_b64 s[2:3], vcc
	s_xor_b64 s[10:11], exec, s[2:3]
	s_cbranch_execz .LBB0_203
	s_add_u32 s12, s8, 0x2400
	s_addc_u32 s13, s9, 0
	s_mov_b32 s2, 0x1000000
	s_mov_b64 s[14:15], 0
	s_branch .LBB0_191

.LBB0_726:
	s_andn2_saveexec_b64 s[2:3], s[10:11]
	s_cbranch_execz .LBB0_759
	s_mov_b64 s[10:11], exec
	v_readlane_b32 s2, v255, 40
	s_nop 0
	s_cmp_lg_u32 s2, 0
	s_cbranch_scc0 .Lfullb_756
	v_mov_b32_e32 v0, 1
	global_atomic_add v231, v0, s[8:9] offset:1024
	s_branch .LBB0_758

.LBB0_1116:
	s_or_b64 exec, exec, s[14:15]
	buffer_inv sc1
	v_cvt_f32_u32_e32 v5, v3
	s_waitcnt vmcnt(1)
	v_readfirstlane_b32 s2, v4
	v_sub_u32_e32 v4, 0, v3
	v_rcp_iflag_f32_e32 v5, v5
	v_add_u32_e32 v6, s2, v0
	v_mul_f32_e32 v5, 0x4f7ffffe, v5
	v_cvt_u32_f32_e32 v5, v5
	v_mul_lo_u32 v0, v4, v5
	v_mul_hi_u32 v0, v5, v0
	v_add_u32_e32 v0, v5, v0
	v_mul_hi_u32 v0, v6, v0
	v_mul_lo_u32 v4, v0, v3
	v_sub_u32_e32 v4, v6, v4
	v_add_u32_e32 v5, 1, v0
	v_cmp_ge_u32_e32 vcc, v4, v3
	s_nop 1
	v_cndmask_b32_e32 v0, v0, v5, vcc
	v_sub_u32_e32 v5, v4, v3
	v_cndmask_b32_e32 v4, v4, v5, vcc
	v_add_u32_e32 v5, 1, v0
	v_cmp_ge_u32_e32 vcc, v4, v3
	v_add_u32_e32 v4, 1, v6
	s_nop 0
	v_cndmask_b32_e32 v0, v0, v5, vcc
	v_mul_lo_u32 v5, v3, v0
	v_add_u32_e32 v3, v5, v3
	v_cmp_ne_u32_e32 vcc, v4, v3
	s_and_saveexec_b64 s[2:3], vcc
	s_xor_b64 s[12:13], exec, s[2:3]
	s_cbranch_execz .LBB0_1139
	s_add_u32 s14, s8, 0x2400
	s_addc_u32 s15, s9, 0
	s_mov_b32 s2, 0x1000000
	s_mov_b64 s[16:17], 0
	s_branch .LBB0_1127

.LBB0_1139:
	s_andn2_saveexec_b64 s[2:3], s[12:13]
	s_cbranch_execz .LBB0_1172
	s_mov_b64 s[12:13], exec
	v_readlane_b32 s2, v255, 40
	s_nop 0
	s_cmp_lg_u32 s2, 0
	s_cbranch_scc0 .Lfullb_1169
	v_mov_b32_e32 v0, 1
	global_atomic_add v231, v0, s[8:9] offset:1024
	s_branch .LBB0_1171

.LBB0_1344:
	s_mov_b64 s[12:13], exec
	v_readlane_b32 s2, v255, 40
	s_and_b64 vcc, exec, s[10:11]
	s_cselect_b32 s3, 1, 0
	s_and_b32 s2, s2, s3
	s_cmp_lg_u32 s2, 0
	s_cbranch_scc0 .Lfullb_1373
	v_mov_b32_e32 v0, 1
	global_atomic_add v231, v0, s[8:9] offset:1024
	s_branch .Lb2_tail
